# P0 weight transpose: a CU's 8 waves take 8 consecutive k-blocks of one n-block (1 KiB store runs per output row)
# baseline (speedup 1.0000x reference)
; #define DUPREP(k) for (int rep_ = 0; rep_ < 1 + ((MK_DUP >> (k)) & 1); ++rep_)
; #define LAS __attribute__((address_space(3)))
; #define LDS_WAIT() asm volatile("s_waitcnt lgkmcnt(0)" ::: "memory")
; __device__ __forceinline__ void p0_transpose_item(const float* W, int K, int N, bf16_t* WT, LAS float* scr, int item, int lane, const float* kscale) {
;     const int nblk = N / 32, kb = item / nblk, nb = item % nblk, k0 = 64 * kb, n0 = 32 * nb;
; #pragma unroll 8
;     for (int i = 0; i < 32; ++i) { const int kk = 2 * i + (lane >> 5); scr[kk * 33 + (lane & 31)] = W[(size_t)(k0 + kk) * N + n0 + (lane & 31)] * (kscale ? kscale[k0 + kk] : 1.0f); }
;     LDS_WAIT(); asm volatile("" ::: "memory");
; __global__ void __launch_bounds__(512, 2) mk_fwd(Params p) {
;     ...
;             constexpr int I1 = (DM / 64) * (DIN / 32), I2 = (DM / 64) * (DM / 32), IL = I1 + I2;
;             DUPREP(0) for (int it = gw; it < DEPTH * IL; it += NGW) {
;                 const int l = it / IL, r = it % IL;
;                 if (r < I1) p0_transpose_item(p.w_in + (size_t)l * DM * DIN, DM, DIN, W1T + (size_t)l * DIN * DM, scr, r, lane, p.norm_w + (size_t)l * DM);
;                 else p0_transpose_item(p.w_out + (size_t)l * DM * DM, DM, DM, W2T + (size_t)l * DM * DM, scr, r - I1, lane, nullptr);
.LBB0_226:
	s_mul_hi_i32 s0, s4, 0x78787879
	s_lshr_b32 s1, s0, 31
	s_ashr_i32 s0, s0, 12
	s_add_i32 s2, s0, s1
	s_mul_i32 s0, s2, 0x2200
	s_sub_i32 s5, s4, s0
	s_ashr_i32 s3, s2, 31
	s_cmpk_gt_i32 s5, 0x19ff
	s_mov_b64 s[0:1], -1
	s_cbranch_scc0 .LBB0_230
	s_and_b32 s6, s5, 7
	s_lshr_b32 s7, s5, 6
	s_and_b32 s7, s7, 7
	s_andn2_b32 s5, s5, 0x1c7
	s_lshl_b32 s6, s6, 6
	s_or_b32 s5, s5, s6
	s_or_b32 s5, s5, s7
	s_lshl_b64 s[0:1], s[2:3], 22
	s_lshl_b64 s[6:7], s[2:3], 24
	s_add_u32 s8, s66, s6
	s_addc_u32 s9, s67, s7
	s_add_i32 s6, s5, 0xe600
	s_and_b32 s7, s6, 0xffc0
	s_lshl_b32 s6, s5, 5
	s_and_b32 s6, s6, 0x7e0
	s_lshl_b32 s10, s6, 2
	s_add_u32 s8, s8, s10
	s_addc_u32 s9, s9, 0
	v_mov_b32_e32 v13, v1
	v_lshl_add_u64 v[14:15], s[8:9], 0, v[12:13]
	v_or_b32_e32 v5, s7, v3
	v_or_b32_e32 v16, s7, v4
	s_lshl_b32 s10, s7, 13
	s_add_u32 s8, s8, s10
	s_addc_u32 s9, s9, 0
	v_lshlrev_b32_e32 v47, 13, v4
	v_add_u32_e32 v47, v47, v12
	global_load_dword v100, v47, s[8:9]
	s_add_u32 s8, s8, 0x4000
	s_addc_u32 s9, s9, 0
	global_load_dword v101, v47, s[8:9]
	s_add_u32 s8, s8, 0x4000
	s_addc_u32 s9, s9, 0
	global_load_dword v102, v47, s[8:9]
	s_add_u32 s8, s8, 0x4000
	s_addc_u32 s9, s9, 0
	global_load_dword v103, v47, s[8:9]
	s_add_u32 s8, s8, 0x4000
	s_addc_u32 s9, s9, 0
	global_load_dword v104, v47, s[8:9]
	s_add_u32 s8, s8, 0x4000
	s_addc_u32 s9, s9, 0
	global_load_dword v105, v47, s[8:9]
	s_add_u32 s8, s8, 0x4000
	s_addc_u32 s9, s9, 0
	global_load_dword v106, v47, s[8:9]
	s_add_u32 s8, s8, 0x4000
	s_addc_u32 s9, s9, 0
	global_load_dword v107, v47, s[8:9]
	s_add_u32 s8, s8, 0x4000
	s_addc_u32 s9, s9, 0
	global_load_dword v108, v47, s[8:9]
	s_add_u32 s8, s8, 0x4000
	s_addc_u32 s9, s9, 0
	global_load_dword v109, v47, s[8:9]
	s_add_u32 s8, s8, 0x4000
	s_addc_u32 s9, s9, 0
	global_load_dword v110, v47, s[8:9]
	s_add_u32 s8, s8, 0x4000
	s_addc_u32 s9, s9, 0
	global_load_dword v111, v47, s[8:9]
	s_add_u32 s8, s8, 0x4000
	s_addc_u32 s9, s9, 0
	global_load_dword v112, v47, s[8:9]
	s_add_u32 s8, s8, 0x4000
	s_addc_u32 s9, s9, 0
	global_load_dword v113, v47, s[8:9]
	s_add_u32 s8, s8, 0x4000
	s_addc_u32 s9, s9, 0
	global_load_dword v114, v47, s[8:9]
	s_add_u32 s8, s8, 0x4000
	s_addc_u32 s9, s9, 0
	global_load_dword v115, v47, s[8:9]
	s_add_u32 s8, s8, 0x4000
	s_addc_u32 s9, s9, 0
	global_load_dword v116, v47, s[8:9]
	s_add_u32 s8, s8, 0x4000
	s_addc_u32 s9, s9, 0
	global_load_dword v117, v47, s[8:9]
	s_add_u32 s8, s8, 0x4000
	s_addc_u32 s9, s9, 0
	global_load_dword v118, v47, s[8:9]
	s_add_u32 s8, s8, 0x4000
	s_addc_u32 s9, s9, 0
	global_load_dword v119, v47, s[8:9]
	s_add_u32 s8, s8, 0x4000
	s_addc_u32 s9, s9, 0
	global_load_dword v120, v47, s[8:9]
	s_add_u32 s8, s8, 0x4000
	s_addc_u32 s9, s9, 0
	global_load_dword v121, v47, s[8:9]
	s_add_u32 s8, s8, 0x4000
	s_addc_u32 s9, s9, 0
	global_load_dword v122, v47, s[8:9]
	s_add_u32 s8, s8, 0x4000
	s_addc_u32 s9, s9, 0
	global_load_dword v123, v47, s[8:9]
	s_add_u32 s8, s8, 0x4000
	s_addc_u32 s9, s9, 0
	global_load_dword v124, v47, s[8:9]
	s_add_u32 s8, s8, 0x4000
	s_addc_u32 s9, s9, 0
	global_load_dword v125, v47, s[8:9]
	s_add_u32 s8, s8, 0x4000
	s_addc_u32 s9, s9, 0
	global_load_dword v126, v47, s[8:9]
	s_add_u32 s8, s8, 0x4000
	s_addc_u32 s9, s9, 0
	global_load_dword v127, v47, s[8:9]
	s_add_u32 s8, s8, 0x4000
	s_addc_u32 s9, s9, 0
	global_load_dword v128, v47, s[8:9]
	s_add_u32 s8, s8, 0x4000
	s_addc_u32 s9, s9, 0
	global_load_dword v129, v47, s[8:9]
	s_add_u32 s8, s8, 0x4000
	s_addc_u32 s9, s9, 0
	global_load_dword v130, v47, s[8:9]
	s_add_u32 s8, s8, 0x4000
	s_addc_u32 s9, s9, 0
	global_load_dword v131, v47, s[8:9]
	s_waitcnt vmcnt(31)
	ds_write_b32 v39, v100 offset:0
	s_waitcnt vmcnt(30)
	ds_write_b32 v39, v101 offset:264
	s_waitcnt vmcnt(29)
	ds_write_b32 v39, v102 offset:528
	s_waitcnt vmcnt(28)
	ds_write_b32 v39, v103 offset:792
	s_waitcnt vmcnt(27)
	ds_write_b32 v39, v104 offset:1056
	s_waitcnt vmcnt(26)
	ds_write_b32 v39, v105 offset:1320
	s_waitcnt vmcnt(25)
	ds_write_b32 v39, v106 offset:1584
	s_waitcnt vmcnt(24)
	ds_write_b32 v39, v107 offset:1848
	s_waitcnt vmcnt(23)
	ds_write_b32 v39, v108 offset:2112
	s_waitcnt vmcnt(22)
	ds_write_b32 v39, v109 offset:2376
	s_waitcnt vmcnt(21)
	ds_write_b32 v39, v110 offset:2640
	s_waitcnt vmcnt(20)
	ds_write_b32 v39, v111 offset:2904
	s_waitcnt vmcnt(19)
	ds_write_b32 v39, v112 offset:3168
	s_waitcnt vmcnt(18)
	ds_write_b32 v39, v113 offset:3432
	s_waitcnt vmcnt(17)
	ds_write_b32 v39, v114 offset:3696
	s_waitcnt vmcnt(16)
	ds_write_b32 v39, v115 offset:3960
	s_waitcnt vmcnt(15)
	ds_write_b32 v39, v116 offset:4224
	s_waitcnt vmcnt(14)
	ds_write_b32 v39, v117 offset:4488
	s_waitcnt vmcnt(13)
	ds_write_b32 v39, v118 offset:4752
	s_waitcnt vmcnt(12)
	ds_write_b32 v39, v119 offset:5016
	s_waitcnt vmcnt(11)
	ds_write_b32 v39, v120 offset:5280
	s_waitcnt vmcnt(10)
	ds_write_b32 v39, v121 offset:5544
	s_waitcnt vmcnt(9)
	ds_write_b32 v39, v122 offset:5808
	s_waitcnt vmcnt(8)
	ds_write_b32 v39, v123 offset:6072
	s_waitcnt vmcnt(7)
	ds_write_b32 v39, v124 offset:6336
	s_waitcnt vmcnt(6)
	ds_write_b32 v39, v125 offset:6600
	s_waitcnt vmcnt(5)
	ds_write_b32 v39, v126 offset:6864
	s_waitcnt vmcnt(4)
	ds_write_b32 v39, v127 offset:7128
	s_waitcnt vmcnt(3)
	ds_write_b32 v39, v128 offset:7392
	s_waitcnt vmcnt(2)
	ds_write_b32 v39, v129 offset:7656
	s_waitcnt vmcnt(1)
	ds_write_b32 v39, v130 offset:7920
	s_waitcnt vmcnt(0)
	ds_write_b32 v39, v131 offset:8184
	s_lshl_b64 s[0:1], s[0:1], 1
	s_add_u32 s0, s96, s0
	s_waitcnt lgkmcnt(0)
; #define LAS __attribute__((address_space(3)))
; #define LDS_WAIT() asm volatile("s_waitcnt lgkmcnt(0)" ::: "memory")
; __device__ __forceinline__ unsigned pk2(float lo, float hi) { unsigned r; asm("v_cvt_pk_bf16_f32 %0, %1, %2" : "=v"(r) : "v"(lo), "v"(hi)); return r; }
; __device__ __forceinline__ void p0_transpose_item(const float* W, int K, int N, bf16_t* WT, LAS float* scr, int item, int lane, const float* kscale) {
;     ...
;     for (int i = 0; i < 32; ++i) { const int kk = 2 * i + (lane >> 5); scr[kk * 33 + (lane & 31)] = W[(size_t)(k0 + kk) * N + n0 + (lane & 31)] * (kscale ? kscale[k0 + kk] : 1.0f); }
;     LDS_WAIT(); asm volatile("" ::: "memory");
;     const int c = lane & 7;
; #pragma unroll
;     for (int j = 0; j < 4; ++j) { const int n = (lane >> 3) + 8 * j; const LAS float* s = scr + (8 * c) * 33 + n;
;         v4u o; o.x = pk2(s[0 * 33], s[1 * 33]); o.y = pk2(s[2 * 33], s[3 * 33]); o.z = pk2(s[4 * 33], s[5 * 33]); o.w = pk2(s[6 * 33], s[7 * 33]);
;         *(v4u*)(WT + (size_t)(n0 + n) * K + k0 + 8 * c) = o; }
;     LDS_WAIT(); asm volatile("" ::: "memory");
; }
; __global__ void __launch_bounds__(512, 2) mk_fwd(Params p) {
;     ...
;                 if (r < I1) p0_transpose_item(p.w_in + (size_t)l * DM * DIN, DM, DIN, W1T + (size_t)l * DIN * DM, scr, r, lane, p.norm_w + (size_t)l * DM);
	s_addc_u32 s1, s97, s1
	s_lshl_b32 s7, s7, 1
	s_add_u32 s0, s0, s7
	ds_read2_b32 v[18:19], v9 offset0:33 offset1:41
	ds_read2_b32 v[20:21], v9 offset1:8
	ds_read2_b32 v[22:23], v9 offset0:66 offset1:74
	ds_read2_b32 v[24:25], v9 offset0:99 offset1:107
	ds_read2_b32 v[26:27], v9 offset0:132 offset1:140
	ds_read2_b32 v[28:29], v9 offset0:165 offset1:173
	ds_read2_b32 v[30:31], v9 offset0:198 offset1:206
	ds_read2_b32 v[32:33], v9 offset0:231 offset1:239
	s_addc_u32 s1, s1, 0
	v_lshlrev_b32_e32 v0, 1, v8
	v_lshl_add_u64 v[34:35], s[0:1], 0, v[0:1]
	v_or_b32_e32 v0, s6, v7
	v_lshlrev_b32_e32 v0, 12, v0
	v_lshl_add_u64 v[48:49], v[34:35], 0, v[0:1]
	s_waitcnt lgkmcnt(6)
	v_cvt_pk_bf16_f32 v14, v20, v18
	s_waitcnt lgkmcnt(4)
	v_cvt_pk_bf16_f32 v15, v22, v24
	s_waitcnt lgkmcnt(2)
	v_cvt_pk_bf16_f32 v16, v26, v28
	s_waitcnt lgkmcnt(0)
	v_cvt_pk_bf16_f32 v17, v30, v32
	global_store_dwordx4 v[48:49], v[14:17], off
	v_or_b32_e32 v0, s6, v36
	v_lshlrev_b32_e32 v0, 12, v0
	v_cvt_pk_bf16_f32 v14, v21, v19
	v_cvt_pk_bf16_f32 v15, v23, v25
	v_cvt_pk_bf16_f32 v16, v27, v29
	v_cvt_pk_bf16_f32 v17, v31, v33
	ds_read2_b32 v[20:21], v9 offset0:16 offset1:24
	ds_read2_b32 v[22:23], v9 offset0:49 offset1:57
	ds_read2_b32 v[24:25], v9 offset0:82 offset1:90
	ds_read2_b32 v[26:27], v9 offset0:115 offset1:123
	ds_read2_b32 v[28:29], v9 offset0:148 offset1:156
	ds_read2_b32 v[30:31], v9 offset0:181 offset1:189
	ds_read2_b32 v[32:33], v9 offset0:214 offset1:222
	ds_read2_b32 v[48:49], v9 offset0:247 offset1:255
	v_lshl_add_u64 v[18:19], v[34:35], 0, v[0:1]
	v_or_b32_e32 v0, s6, v37
	v_lshlrev_b32_e32 v0, 12, v0
	global_store_dwordx4 v[18:19], v[14:17], off
	v_lshl_add_u64 v[18:19], v[34:35], 0, v[0:1]
	v_or_b32_e32 v0, s6, v38
	v_lshlrev_b32_e32 v0, 12, v0
	s_waitcnt lgkmcnt(6)
	v_cvt_pk_bf16_f32 v14, v20, v22
	s_waitcnt lgkmcnt(4)
	v_cvt_pk_bf16_f32 v15, v24, v26
	s_waitcnt lgkmcnt(2)
	v_cvt_pk_bf16_f32 v16, v28, v30
	s_waitcnt lgkmcnt(0)
	v_cvt_pk_bf16_f32 v17, v32, v48
	global_store_dwordx4 v[18:19], v[14:17], off
	v_lshl_add_u64 v[18:19], v[34:35], 0, v[0:1]
	s_nop 0
	v_cvt_pk_bf16_f32 v14, v21, v23
	v_cvt_pk_bf16_f32 v15, v25, v27
	v_cvt_pk_bf16_f32 v16, v29, v31
	v_cvt_pk_bf16_f32 v17, v33, v49
	global_store_dwordx4 v[18:19], v[14:17], off
	s_waitcnt lgkmcnt(0)
	s_branch .LBB0_225
.LBB0_230:
	s_and_b64 vcc, exec, s[0:1]
	s_cbranch_vccz .LBB0_225
	s_lshl_b64 s[0:1], s[2:3], 13
	s_add_u32 s18, s54, s0
	s_mul_i32 s0, s5, 0x4ec5
	s_addc_u32 s19, s55, s1
	s_lshr_b32 s1, s0, 31
	s_ashr_i32 s0, s0, 22
	s_add_i32 s0, s0, s1
	s_mul_i32 s1, s0, 0xd0
	s_sub_i32 s1, s5, s1
	s_sext_i32_i16 s1, s1
	s_and_b32 s6, s0, 7
	s_and_b32 s7, s1, 7
	s_andn2_b32 s0, s0, 7
	s_andn2_b32 s1, s1, 7
	s_or_b32 s0, s0, s7
	s_or_b32 s1, s1, s6
	s_lshl_b32 s16, s1, 5
	s_lshl_b32 s20, s0, 6
	s_ashr_i32 s17, s16, 31
	s_mul_i32 s7, s2, 0x3400000
	s_ashr_i32 s21, s20, 31
	s_lshl_b64 s[0:1], s[16:17], 2
	s_mul_hi_i32 s6, s2, 0x3400000
	s_add_u32 s0, s0, s7
	s_addc_u32 s1, s1, s6
	s_mul_i32 s8, s20, 0x6800
	s_add_u32 s6, s56, s0
	s_addc_u32 s7, s57, s1
	s_add_u32 s6, s6, s8
	s_addc_u32 s7, s7, 0
	v_mov_b32_e32 v47, 0x6800
	v_mad_u32_u24 v47, v4, v47, v12
	v_or_b32_e32 v32, s20, v4
	v_lshlrev_b32_e32 v32, 2, v32
	v_mov_b32_e32 v33, v1
	v_lshl_add_u64 v[32:33], s[18:19], 0, v[32:33]
	global_load_dword v100, v47, s[6:7]
	s_add_u32 s6, s6, 0xd000
	s_addc_u32 s7, s7, 0
	global_load_dword v132, v[32:33], off offset:0
	global_load_dword v101, v47, s[6:7]
	s_add_u32 s6, s6, 0xd000
	s_addc_u32 s7, s7, 0
	global_load_dword v133, v[32:33], off offset:8
	global_load_dword v102, v47, s[6:7]
	s_add_u32 s6, s6, 0xd000
	s_addc_u32 s7, s7, 0
	global_load_dword v134, v[32:33], off offset:16
	global_load_dword v103, v47, s[6:7]
	s_add_u32 s6, s6, 0xd000
	s_addc_u32 s7, s7, 0
	global_load_dword v135, v[32:33], off offset:24
	global_load_dword v104, v47, s[6:7]
	s_add_u32 s6, s6, 0xd000
	s_addc_u32 s7, s7, 0
	global_load_dword v136, v[32:33], off offset:32
	global_load_dword v105, v47, s[6:7]
	s_add_u32 s6, s6, 0xd000
	s_addc_u32 s7, s7, 0
	global_load_dword v137, v[32:33], off offset:40
	global_load_dword v106, v47, s[6:7]
	s_add_u32 s6, s6, 0xd000
	s_addc_u32 s7, s7, 0
	global_load_dword v138, v[32:33], off offset:48
	global_load_dword v107, v47, s[6:7]
	s_add_u32 s6, s6, 0xd000
	s_addc_u32 s7, s7, 0
	global_load_dword v139, v[32:33], off offset:56
	global_load_dword v108, v47, s[6:7]
	s_add_u32 s6, s6, 0xd000
	s_addc_u32 s7, s7, 0
	global_load_dword v140, v[32:33], off offset:64
	global_load_dword v109, v47, s[6:7]
	s_add_u32 s6, s6, 0xd000
	s_addc_u32 s7, s7, 0
	global_load_dword v141, v[32:33], off offset:72
	global_load_dword v110, v47, s[6:7]
	s_add_u32 s6, s6, 0xd000
	s_addc_u32 s7, s7, 0
	global_load_dword v142, v[32:33], off offset:80
	global_load_dword v111, v47, s[6:7]
	s_add_u32 s6, s6, 0xd000
	s_addc_u32 s7, s7, 0
	global_load_dword v143, v[32:33], off offset:88
	global_load_dword v112, v47, s[6:7]
	s_add_u32 s6, s6, 0xd000
	s_addc_u32 s7, s7, 0
	global_load_dword v144, v[32:33], off offset:96
	global_load_dword v113, v47, s[6:7]
	s_add_u32 s6, s6, 0xd000
	s_addc_u32 s7, s7, 0
	global_load_dword v145, v[32:33], off offset:104
	global_load_dword v114, v47, s[6:7]
	s_add_u32 s6, s6, 0xd000
	s_addc_u32 s7, s7, 0
	global_load_dword v146, v[32:33], off offset:112
	global_load_dword v115, v47, s[6:7]
	s_add_u32 s6, s6, 0xd000
	s_addc_u32 s7, s7, 0
	global_load_dword v147, v[32:33], off offset:120
	global_load_dword v116, v47, s[6:7]
	s_add_u32 s6, s6, 0xd000
	s_addc_u32 s7, s7, 0
	global_load_dword v148, v[32:33], off offset:128
	s_waitcnt vmcnt(32)
; __device__ __forceinline__ void p0_transpose_item(const float* W, int K, int N, bf16_t* WT, LAS float* scr, int item, int lane, const float* kscale) {
;     ...
;     for (int i = 0; i < 32; ++i) { const int kk = 2 * i + (lane >> 5); scr[kk * 33 + (lane & 31)] = W[(size_t)(k0 + kk) * N + n0 + (lane & 31)] * (kscale ? kscale[k0 + kk] : 1.0f); }
	v_mul_f32_e32 v100, v100, v132
	ds_write_b32 v39, v100 offset:0
	global_load_dword v117, v47, s[6:7]
	s_add_u32 s6, s6, 0xd000
	s_addc_u32 s7, s7, 0
	global_load_dword v149, v[32:33], off offset:136
	s_waitcnt vmcnt(32)
	v_mul_f32_e32 v101, v101, v133
	ds_write_b32 v39, v101 offset:264
	global_load_dword v118, v47, s[6:7]
	s_add_u32 s6, s6, 0xd000
	s_addc_u32 s7, s7, 0
	global_load_dword v150, v[32:33], off offset:144
	s_waitcnt vmcnt(32)
	v_mul_f32_e32 v102, v102, v134
	ds_write_b32 v39, v102 offset:528
	global_load_dword v119, v47, s[6:7]
	s_add_u32 s6, s6, 0xd000
	s_addc_u32 s7, s7, 0
	global_load_dword v151, v[32:33], off offset:152
	s_waitcnt vmcnt(32)
	v_mul_f32_e32 v103, v103, v135
	ds_write_b32 v39, v103 offset:792
	global_load_dword v120, v47, s[6:7]
	s_add_u32 s6, s6, 0xd000
	s_addc_u32 s7, s7, 0
	global_load_dword v152, v[32:33], off offset:160
	s_waitcnt vmcnt(32)
	v_mul_f32_e32 v104, v104, v136
	ds_write_b32 v39, v104 offset:1056
	global_load_dword v121, v47, s[6:7]
	s_add_u32 s6, s6, 0xd000
	s_addc_u32 s7, s7, 0
	global_load_dword v153, v[32:33], off offset:168
	s_waitcnt vmcnt(32)
	v_mul_f32_e32 v105, v105, v137
	ds_write_b32 v39, v105 offset:1320
	global_load_dword v122, v47, s[6:7]
	s_add_u32 s6, s6, 0xd000
	s_addc_u32 s7, s7, 0
	global_load_dword v154, v[32:33], off offset:176
	s_waitcnt vmcnt(32)
	v_mul_f32_e32 v106, v106, v138
	ds_write_b32 v39, v106 offset:1584
	global_load_dword v123, v47, s[6:7]
	s_add_u32 s6, s6, 0xd000
	s_addc_u32 s7, s7, 0
	global_load_dword v155, v[32:33], off offset:184
	s_waitcnt vmcnt(32)
	v_mul_f32_e32 v107, v107, v139
	ds_write_b32 v39, v107 offset:1848
	global_load_dword v124, v47, s[6:7]
	s_add_u32 s6, s6, 0xd000
	s_addc_u32 s7, s7, 0
	global_load_dword v156, v[32:33], off offset:192
	s_waitcnt vmcnt(32)
	v_mul_f32_e32 v108, v108, v140
	ds_write_b32 v39, v108 offset:2112
	global_load_dword v125, v47, s[6:7]
	s_add_u32 s6, s6, 0xd000
	s_addc_u32 s7, s7, 0
	global_load_dword v157, v[32:33], off offset:200
	s_waitcnt vmcnt(32)
	v_mul_f32_e32 v109, v109, v141
	ds_write_b32 v39, v109 offset:2376
	global_load_dword v126, v47, s[6:7]
	s_add_u32 s6, s6, 0xd000
	s_addc_u32 s7, s7, 0
	global_load_dword v158, v[32:33], off offset:208
	s_waitcnt vmcnt(32)
	v_mul_f32_e32 v110, v110, v142
	ds_write_b32 v39, v110 offset:2640
	global_load_dword v127, v47, s[6:7]
	s_add_u32 s6, s6, 0xd000
	s_addc_u32 s7, s7, 0
	global_load_dword v159, v[32:33], off offset:216
	s_waitcnt vmcnt(32)
	v_mul_f32_e32 v111, v111, v143
	ds_write_b32 v39, v111 offset:2904
	global_load_dword v128, v47, s[6:7]
	s_add_u32 s6, s6, 0xd000
	s_addc_u32 s7, s7, 0
	global_load_dword v160, v[32:33], off offset:224
	s_waitcnt vmcnt(32)
	v_mul_f32_e32 v112, v112, v144
	ds_write_b32 v39, v112 offset:3168
	global_load_dword v129, v47, s[6:7]
	s_add_u32 s6, s6, 0xd000
	s_addc_u32 s7, s7, 0
	global_load_dword v161, v[32:33], off offset:232
	s_waitcnt vmcnt(32)
	v_mul_f32_e32 v113, v113, v145
	ds_write_b32 v39, v113 offset:3432
	global_load_dword v130, v47, s[6:7]
	s_add_u32 s6, s6, 0xd000
	s_addc_u32 s7, s7, 0
	global_load_dword v162, v[32:33], off offset:240
	s_waitcnt vmcnt(32)
	v_mul_f32_e32 v114, v114, v146
	ds_write_b32 v39, v114 offset:3696
	global_load_dword v131, v47, s[6:7]
	global_load_dword v163, v[32:33], off offset:248
	s_waitcnt vmcnt(32)
	v_mul_f32_e32 v115, v115, v147
	ds_write_b32 v39, v115 offset:3960
	s_waitcnt vmcnt(30)
	v_mul_f32_e32 v116, v116, v148
	ds_write_b32 v39, v116 offset:4224
	s_waitcnt vmcnt(28)
	v_mul_f32_e32 v117, v117, v149
	ds_write_b32 v39, v117 offset:4488
	s_waitcnt vmcnt(26)
	v_mul_f32_e32 v118, v118, v150
	ds_write_b32 v39, v118 offset:4752
	s_waitcnt vmcnt(24)
	v_mul_f32_e32 v119, v119, v151
	ds_write_b32 v39, v119 offset:5016
	s_waitcnt vmcnt(22)
	v_mul_f32_e32 v120, v120, v152
	ds_write_b32 v39, v120 offset:5280
	s_waitcnt vmcnt(20)
	v_mul_f32_e32 v121, v121, v153
	ds_write_b32 v39, v121 offset:5544
	s_waitcnt vmcnt(18)
	v_mul_f32_e32 v122, v122, v154
	ds_write_b32 v39, v122 offset:5808
	s_waitcnt vmcnt(16)
	v_mul_f32_e32 v123, v123, v155
	ds_write_b32 v39, v123 offset:6072
	s_waitcnt vmcnt(14)
	v_mul_f32_e32 v124, v124, v156
	ds_write_b32 v39, v124 offset:6336
	s_waitcnt vmcnt(12)
	v_mul_f32_e32 v125, v125, v157
	ds_write_b32 v39, v125 offset:6600
	s_waitcnt vmcnt(10)
	v_mul_f32_e32 v126, v126, v158
	ds_write_b32 v39, v126 offset:6864
	s_waitcnt vmcnt(8)
	v_mul_f32_e32 v127, v127, v159
	ds_write_b32 v39, v127 offset:7128
	s_waitcnt vmcnt(6)
	v_mul_f32_e32 v128, v128, v160
	ds_write_b32 v39, v128 offset:7392
	s_waitcnt vmcnt(4)
	v_mul_f32_e32 v129, v129, v161
	ds_write_b32 v39, v129 offset:7656
	s_waitcnt vmcnt(2)
	v_mul_f32_e32 v130, v130, v162
	ds_write_b32 v39, v130 offset:7920
	s_waitcnt vmcnt(0)
	v_mul_f32_e32 v131, v131, v163
	ds_write_b32 v39, v131 offset:8184
	s_branch .LBB0_224
